# W2 GEMM K-loop: next A tile loaded global->LDS directly (global_load_lds_dwordx4, source-side XOR swizzle), no register staging / LDS stores
# speedup vs baseline: 1.0550x; 1.0129x over previous
; #define MFMA16(a, b, c) __builtin_amdgcn_mfma_f32_16x16x32_bf16((a), (b), (c), 0, 0, 0)
; template <class Epi>
; DEVI void gemm_tile256b(const bf16_t* __restrict__ A, int lda, const bf16_t* __restrict__ Bt, int K,
;                         int m0, int n0, char* smem, Epi epi) {
;     ...
;   for (int kt = 0; kt < nk; ++kt) {
;     const char* base = smem + (kt & 1) * 32768;
;     const bool more = kt + 1 < nk;
;     if (more) {
; #pragma unroll
;       for (int i = 0; i < 8; ++i) ra[i] = *(const u32x4*)(ag + (size_t)(i * 32) * lda + (kt + 1) * 64);
;     }
; #pragma unroll
;     for (int i = 0; i < 4; ++i) b1[i] = *(const bf16x8*)(bp + ((size_t)i * kb32 + kt * 2 + 1) * 512);
;     {
;       bf16x8 af[8];
; #pragma unroll
;       for (int i = 0; i < 8; ++i) af[i] = *(const bf16x8*)(base + a_rd + i * 2048);
; #pragma unroll
;       for (int mi = 0; mi < 8; ++mi)
; #pragma unroll
;         for (int ni = 0; ni < 4; ++ni) acc[mi][ni] = MFMA16(b0[ni], af[mi], acc[mi][ni]);
;     }
;     if (more) {
; #pragma unroll
;       for (int i = 0; i < 4; ++i) b0[i] = *(const bf16x8*)(bp + ((size_t)i * kb32 + kt * 2 + 2) * 512);
;     }
;     {
;       bf16x8 af[8];
; #pragma unroll
;       for (int i = 0; i < 8; ++i) af[i] = *(const bf16x8*)(base + ((a_rd + i * 2048) ^ 64));
; #pragma unroll
;       for (int mi = 0; mi < 8; ++mi)
; #pragma unroll
;         for (int ni = 0; ni < 4; ++ni) acc[mi][ni] = MFMA16(b1[ni], af[mi], acc[mi][ni]);
;     }
;     if (more) {
;       char* nb = smem + ((kt + 1) & 1) * 32768 + lds_w;
; #pragma unroll
;       for (int i = 0; i < 8; ++i) *(u32x4*)(nb + i * 4096) = ra[i];
.LBB0_1838:
	s_add_i32 s13, s1, 0xffff8000
	s_and_b32 s13, s13, 0x8000
	s_add_i32 s13, s13, 32
	v_add_u32_e32 v0, s13, v173
	ds_read_b128 v[146:149], v0
	ds_read_b128 v[150:153], v0 offset:2048
	v_lshl_add_u64 v[154:155], v[164:165], 0, s[28:29]
	s_mov_b32 s16, 0x3280000
	v_add_co_u32_e32 v156, vcc, s16, v154
	s_waitcnt vmcnt(3) lgkmcnt(1)
	v_mfma_f32_16x16x32_bf16 v[122:125], v[14:17], v[146:149], v[122:125]
	v_addc_co_u32_e32 v157, vcc, 0, v155, vcc
	s_mov_b32 s16, 0x32a0000
	s_waitcnt vmcnt(2)
	v_mfma_f32_16x16x32_bf16 v[114:117], v[10:13], v[146:149], v[114:117]
	v_add_co_u32_e32 v158, vcc, s16, v154
	s_mov_b32 s16, 0x32c0000
	s_waitcnt vmcnt(1)
	v_mfma_f32_16x16x32_bf16 v[110:113], v[6:9], v[146:149], v[110:113]
	v_addc_co_u32_e32 v159, vcc, 0, v155, vcc
	v_add_co_u32_e32 v160, vcc, s16, v154
	s_waitcnt vmcnt(0)
	v_mfma_f32_16x16x32_bf16 v[106:109], v[2:5], v[146:149], v[106:109]
	v_addc_co_u32_e32 v161, vcc, 0, v155, vcc
	s_mov_b32 s16, 0x32e0000
	s_waitcnt lgkmcnt(0)
	v_mfma_f32_16x16x32_bf16 v[102:105], v[14:17], v[150:153], v[102:105]
	v_add_co_u32_e32 v182, vcc, s16, v154
	v_lshl_add_u64 v[164:165], v[164:165], 0, s[64:65]
	v_mfma_f32_16x16x32_bf16 v[90:93], v[10:13], v[150:153], v[90:93]
	v_addc_co_u32_e32 v183, vcc, 0, v155, vcc
	v_mfma_f32_16x16x32_bf16 v[78:81], v[6:9], v[150:153], v[78:81]
	v_mfma_f32_16x16x32_bf16 v[74:77], v[2:5], v[150:153], v[74:77]
	ds_read_b128 v[146:149], v0 offset:4096
	ds_read_b128 v[150:153], v0 offset:6144
	s_waitcnt lgkmcnt(1)
	v_mfma_f32_16x16x32_bf16 v[70:73], v[14:17], v[146:149], v[70:73]
	v_mfma_f32_16x16x32_bf16 v[66:69], v[10:13], v[146:149], v[66:69]
	v_mfma_f32_16x16x32_bf16 v[58:61], v[6:9], v[146:149], v[58:61]
	v_mfma_f32_16x16x32_bf16 v[46:49], v[2:5], v[146:149], v[46:49]
	s_waitcnt lgkmcnt(0)
	v_mfma_f32_16x16x32_bf16 v[34:37], v[14:17], v[150:153], v[34:37]
	v_mfma_f32_16x16x32_bf16 v[22:25], v[10:13], v[150:153], v[22:25]
	v_mfma_f32_16x16x32_bf16 v[30:33], v[6:9], v[150:153], v[30:33]
	v_mfma_f32_16x16x32_bf16 v[42:45], v[2:5], v[150:153], v[42:45]
	ds_read_b128 v[146:149], v0 offset:8192
	ds_read_b128 v[150:153], v0 offset:10240
	s_waitcnt lgkmcnt(1)
	v_mfma_f32_16x16x32_bf16 v[18:21], v[14:17], v[146:149], v[18:21]
	v_mfma_f32_16x16x32_bf16 v[26:29], v[10:13], v[146:149], v[26:29]
	v_mfma_f32_16x16x32_bf16 v[38:41], v[6:9], v[146:149], v[38:41]
	v_mfma_f32_16x16x32_bf16 v[50:53], v[2:5], v[146:149], v[50:53]
	s_waitcnt lgkmcnt(0)
	v_mfma_f32_16x16x32_bf16 v[54:57], v[14:17], v[150:153], v[54:57]
	v_mfma_f32_16x16x32_bf16 v[62:65], v[10:13], v[150:153], v[62:65]
	v_mfma_f32_16x16x32_bf16 v[98:101], v[6:9], v[150:153], v[98:101]
	v_mfma_f32_16x16x32_bf16 v[118:121], v[2:5], v[150:153], v[118:121]
	ds_read_b128 v[146:149], v0 offset:12288
	ds_read_b128 v[150:153], v0 offset:14336
	v_add_u32_e32 v0, s13, v171
	s_waitcnt lgkmcnt(1)
	v_mfma_f32_16x16x32_bf16 v[86:89], v[14:17], v[146:149], v[86:89]
	v_mfma_f32_16x16x32_bf16 v[94:97], v[10:13], v[146:149], v[94:97]
	v_mfma_f32_16x16x32_bf16 v[82:85], v[6:9], v[146:149], v[82:85]
	v_mfma_f32_16x16x32_bf16 v[142:145], v[2:5], v[146:149], v[142:145]
	global_load_dwordx4 v[146:149], v[156:157], off offset:1024
	ds_read_b128 v[174:177], v0
	ds_read_b128 v[178:181], v0 offset:2048
	s_waitcnt lgkmcnt(2)
	v_mfma_f32_16x16x32_bf16 v[138:141], v[14:17], v[150:153], v[138:141]
	global_load_dwordx4 v[14:17], v[156:157], off offset:2048
	v_mfma_f32_16x16x32_bf16 v[134:137], v[10:13], v[150:153], v[134:137]
	v_mfma_f32_16x16x32_bf16 v[130:133], v[6:9], v[150:153], v[130:133]
	v_mfma_f32_16x16x32_bf16 v[126:129], v[2:5], v[150:153], v[126:129]
	global_load_dwordx4 v[150:153], v[158:159], off offset:1024
	global_load_dwordx4 v[10:13], v[158:159], off offset:2048
	global_load_dwordx4 v[154:157], v[160:161], off offset:1024
	global_load_dwordx4 v[6:9], v[160:161], off offset:2048
	s_nop 0
	global_load_dwordx4 v[158:161], v[182:183], off offset:1024
	global_load_dwordx4 v[2:5], v[182:183], off offset:2048
	v_lshrrev_b32_e32 v195, 6, v206
	v_lshl_add_u64 v[190:191], v[166:167], 0, s[28:29]
	v_lshrrev_b32_e32 v194, 3, v206
	v_readfirstlane_b32 s99, v195
	v_and_b32_e32 v194, 7, v194
	s_and_b32 s98, s1, 0x8000
	v_lshlrev_b32_e32 v194, 4, v194
	s_lshl_b32 s99, s99, 10
	v_xor_b32_e32 v190, v194, v190
	s_add_u32 s98, s98, s99
	s_add_u32 s98, s98, 32
	s_mov_b32 s101, 0
	s_mov_b32 s100, 0x3b93080
	v_lshl_add_u64 v[192:193], v[190:191], 0, s[100:101]
	s_mov_b32 m0, s98
	s_nop 0
	global_load_lds_dwordx4 v[192:193], off
	s_mov_b32 s100, 0x3bd3080
	v_lshl_add_u64 v[192:193], v[190:191], 0, s[100:101]
	s_add_u32 m0, s98, 0x1000
	s_nop 0
	global_load_lds_dwordx4 v[192:193], off
	s_mov_b32 s100, 0x3c13080
	v_lshl_add_u64 v[192:193], v[190:191], 0, s[100:101]
	s_add_u32 m0, s98, 0x2000
	s_nop 0
	global_load_lds_dwordx4 v[192:193], off
	s_mov_b32 s100, 0x3c53080
	v_lshl_add_u64 v[192:193], v[190:191], 0, s[100:101]
	s_add_u32 m0, s98, 0x3000
	s_nop 0
	global_load_lds_dwordx4 v[192:193], off
	s_mov_b32 s100, 0x3c93080
	v_lshl_add_u64 v[192:193], v[190:191], 0, s[100:101]
	s_add_u32 m0, s98, 0x4000
	s_nop 0
	global_load_lds_dwordx4 v[192:193], off
	s_mov_b32 s100, 0x3cd3080
	v_lshl_add_u64 v[192:193], v[190:191], 0, s[100:101]
	s_add_u32 m0, s98, 0x5000
	s_nop 0
	global_load_lds_dwordx4 v[192:193], off
	s_mov_b32 s100, 0x3d13080
	v_lshl_add_u64 v[192:193], v[190:191], 0, s[100:101]
	s_add_u32 m0, s98, 0x6000
	s_nop 0
	global_load_lds_dwordx4 v[192:193], off
	s_mov_b32 s100, 0x3d53080
	v_lshl_add_u64 v[192:193], v[190:191], 0, s[100:101]
	s_add_u32 m0, s98, 0x7000
	s_nop 0
	global_load_lds_dwordx4 v[192:193], off
	s_nop 0
	s_nop 0
	s_waitcnt vmcnt(15) lgkmcnt(1)
; #define MFMA16(a, b, c) __builtin_amdgcn_mfma_f32_16x16x32_bf16((a), (b), (c), 0, 0, 0)
; template <class Epi>
; DEVI void gemm_tile256b(const bf16_t* __restrict__ A, int lda, const bf16_t* __restrict__ Bt, int K,
;                         int m0, int n0, char* smem, Epi epi) {
;     ...
;     if (more) {
; #pragma unroll
;       for (int i = 0; i < 4; ++i) b0[i] = *(const bf16x8*)(bp + ((size_t)i * kb32 + kt * 2 + 2) * 512);
;     }
;     {
;       bf16x8 af[8];
; #pragma unroll
;       for (int i = 0; i < 8; ++i) af[i] = *(const bf16x8*)(base + ((a_rd + i * 2048) ^ 64));
; #pragma unroll
;       for (int mi = 0; mi < 8; ++mi)
; #pragma unroll
;         for (int ni = 0; ni < 4; ++ni) acc[mi][ni] = MFMA16(b1[ni], af[mi], acc[mi][ni]);
;     }
;     if (more) {
;       char* nb = smem + ((kt + 1) & 1) * 32768 + lds_w;
; #pragma unroll
;       for (int i = 0; i < 8; ++i) *(u32x4*)(nb + i * 4096) = ra[i];
;     }
;     __syncthreads();
	v_mfma_f32_16x16x32_bf16 v[122:125], v[146:149], v[174:177], v[122:125]
	s_waitcnt vmcnt(13)
	v_mfma_f32_16x16x32_bf16 v[114:117], v[150:153], v[174:177], v[114:117]
	s_waitcnt vmcnt(11)
	v_mfma_f32_16x16x32_bf16 v[110:113], v[154:157], v[174:177], v[110:113]
	s_waitcnt vmcnt(9)
	v_mfma_f32_16x16x32_bf16 v[106:109], v[158:161], v[174:177], v[106:109]
	s_waitcnt lgkmcnt(0)
	v_mfma_f32_16x16x32_bf16 v[102:105], v[146:149], v[178:181], v[102:105]
	v_mfma_f32_16x16x32_bf16 v[90:93], v[150:153], v[178:181], v[90:93]
	v_mfma_f32_16x16x32_bf16 v[78:81], v[154:157], v[178:181], v[78:81]
	s_nop 0
	v_mfma_f32_16x16x32_bf16 v[74:77], v[158:161], v[178:181], v[74:77]
	ds_read_b128 v[174:177], v0 offset:4096
	ds_read_b128 v[178:181], v0 offset:6144
	s_waitcnt lgkmcnt(1)
	v_mfma_f32_16x16x32_bf16 v[70:73], v[146:149], v[174:177], v[70:73]
	s_and_b32 s13, s1, 0x8000
	v_mfma_f32_16x16x32_bf16 v[66:69], v[150:153], v[174:177], v[66:69]
	s_add_i32 s1, s1, 0x8000
	v_lshl_add_u64 v[166:167], v[166:167], 0, s[60:61]
	s_cmp_eq_u32 s1, 0x200000
	v_mfma_f32_16x16x32_bf16 v[58:61], v[154:157], v[174:177], v[58:61]
	v_mfma_f32_16x16x32_bf16 v[46:49], v[158:161], v[174:177], v[46:49]
	s_waitcnt lgkmcnt(0)
	v_mfma_f32_16x16x32_bf16 v[34:37], v[146:149], v[178:181], v[34:37]
	v_mfma_f32_16x16x32_bf16 v[22:25], v[150:153], v[178:181], v[22:25]
	v_mfma_f32_16x16x32_bf16 v[30:33], v[154:157], v[178:181], v[30:33]
	v_mfma_f32_16x16x32_bf16 v[42:45], v[158:161], v[178:181], v[42:45]
	ds_read_b128 v[174:177], v0 offset:8192
	ds_read_b128 v[178:181], v0 offset:10240
	s_waitcnt lgkmcnt(1)
	v_mfma_f32_16x16x32_bf16 v[18:21], v[146:149], v[174:177], v[18:21]
	v_mfma_f32_16x16x32_bf16 v[26:29], v[150:153], v[174:177], v[26:29]
	v_mfma_f32_16x16x32_bf16 v[38:41], v[154:157], v[174:177], v[38:41]
	v_mfma_f32_16x16x32_bf16 v[50:53], v[158:161], v[174:177], v[50:53]
	s_waitcnt lgkmcnt(0)
	v_mfma_f32_16x16x32_bf16 v[54:57], v[146:149], v[178:181], v[54:57]
	v_mfma_f32_16x16x32_bf16 v[62:65], v[150:153], v[178:181], v[62:65]
	v_mfma_f32_16x16x32_bf16 v[98:101], v[154:157], v[178:181], v[98:101]
	v_mfma_f32_16x16x32_bf16 v[118:121], v[158:161], v[178:181], v[118:121]
	ds_read_b128 v[178:181], v0 offset:12288
	ds_read_b128 v[182:185], v0 offset:14336
	s_nop 0
	s_nop 0
	s_nop 0
	s_nop 0
	s_nop 0
	s_waitcnt lgkmcnt(1)
	v_mfma_f32_16x16x32_bf16 v[86:89], v[146:149], v[178:181], v[86:89]
	v_mfma_f32_16x16x32_bf16 v[94:97], v[150:153], v[178:181], v[94:97]
	v_mfma_f32_16x16x32_bf16 v[82:85], v[154:157], v[178:181], v[82:85]
	s_waitcnt vmcnt(0) lgkmcnt(0)
	s_barrier
	v_mfma_f32_16x16x32_bf16 v[142:145], v[158:161], v[178:181], v[142:145]
	v_mfma_f32_16x16x32_bf16 v[138:141], v[146:149], v[182:185], v[138:141]
	v_mfma_f32_16x16x32_bf16 v[134:137], v[150:153], v[182:185], v[134:137]
	v_mfma_f32_16x16x32_bf16 v[130:133], v[154:157], v[182:185], v[130:133]
	v_mfma_f32_16x16x32_bf16 v[126:129], v[158:161], v[182:185], v[126:129]
	s_cbranch_scc0 .LBB0_1838
	v_add_u32_e32 v0, 32, v173
	ds_read_b128 v[146:149], v0 offset:32768
	ds_read_b128 v[150:153], v0 offset:34816
	s_waitcnt lgkmcnt(1)
	v_mfma_f32_16x16x32_bf16 v[122:125], v[14:17], v[146:149], v[122:125]
	v_mfma_f32_16x16x32_bf16 v[114:117], v[10:13], v[146:149], v[114:117]
	v_mfma_f32_16x16x32_bf16 v[110:113], v[6:9], v[146:149], v[110:113]
	v_mfma_f32_16x16x32_bf16 v[106:109], v[2:5], v[146:149], v[106:109]
	s_waitcnt lgkmcnt(0)
	v_mfma_f32_16x16x32_bf16 v[102:105], v[14:17], v[150:153], v[102:105]
	v_mfma_f32_16x16x32_bf16 v[90:93], v[10:13], v[150:153], v[90:93]
	v_mfma_f32_16x16x32_bf16 v[78:81], v[6:9], v[150:153], v[78:81]
	v_mfma_f32_16x16x32_bf16 v[74:77], v[2:5], v[150:153], v[74:77]
	ds_read_b128 v[146:149], v0 offset:36864
	ds_read_b128 v[150:153], v0 offset:38912
	s_waitcnt lgkmcnt(1)
	v_mfma_f32_16x16x32_bf16 v[70:73], v[14:17], v[146:149], v[70:73]
	v_mfma_f32_16x16x32_bf16 v[66:69], v[10:13], v[146:149], v[66:69]
	v_mfma_f32_16x16x32_bf16 v[58:61], v[6:9], v[146:149], v[58:61]
	v_mfma_f32_16x16x32_bf16 v[46:49], v[2:5], v[146:149], v[46:49]
	s_waitcnt lgkmcnt(0)
	v_mfma_f32_16x16x32_bf16 v[34:37], v[14:17], v[150:153], v[34:37]
	v_mfma_f32_16x16x32_bf16 v[22:25], v[10:13], v[150:153], v[22:25]
	v_mfma_f32_16x16x32_bf16 v[30:33], v[6:9], v[150:153], v[30:33]
	v_mfma_f32_16x16x32_bf16 v[42:45], v[2:5], v[150:153], v[42:45]
	ds_read_b128 v[146:149], v0 offset:40960
	ds_read_b128 v[150:153], v0 offset:43008
	s_waitcnt lgkmcnt(1)
	v_mfma_f32_16x16x32_bf16 v[18:21], v[14:17], v[146:149], v[18:21]
	v_mfma_f32_16x16x32_bf16 v[26:29], v[10:13], v[146:149], v[26:29]
	v_mfma_f32_16x16x32_bf16 v[38:41], v[6:9], v[146:149], v[38:41]
	v_mfma_f32_16x16x32_bf16 v[50:53], v[2:5], v[146:149], v[50:53]
	s_waitcnt lgkmcnt(0)
	v_mfma_f32_16x16x32_bf16 v[146:149], v[14:17], v[150:153], v[54:57]
	v_mfma_f32_16x16x32_bf16 v[154:157], v[10:13], v[150:153], v[62:65]
	s_nop 1
	ds_read_b128 v[54:57], v0 offset:45056
	ds_read_b128 v[62:65], v0 offset:47104
	v_add_u32_e32 v0, 32, v171
	s_waitcnt lgkmcnt(1)
	v_mfma_f32_16x16x32_bf16 v[176:179], v[6:9], v[54:57], v[82:85]
	s_nop 2
	v_add_co_u32_e32 v82, vcc, 0x1f000, v162
	v_mfma_f32_16x16x32_bf16 v[164:167], v[14:17], v[54:57], v[86:89]
	s_nop 0
	v_addc_co_u32_e32 v83, vcc, 0, v163, vcc
	v_mfma_f32_16x16x32_bf16 v[172:175], v[10:13], v[54:57], v[94:97]
	v_mfma_f32_16x16x32_bf16 v[142:145], v[2:5], v[54:57], v[142:145]
	v_add_co_u32_e32 v54, vcc, 0x3f000, v162
	s_nop 1
	v_addc_co_u32_e32 v55, vcc, 0, v163, vcc
	s_waitcnt lgkmcnt(0)
; #define MFMA16(a, b, c) __builtin_amdgcn_mfma_f32_16x16x32_bf16((a), (b), (c), 0, 0, 0)
; template <class Epi>
; DEVI void gemm_tile256b(const bf16_t* __restrict__ A, int lda, const bf16_t* __restrict__ Bt, int K,
;                         int m0, int n0, char* smem, Epi epi) {
;     ...
;     {
;       bf16x8 af[8];
; #pragma unroll
;       for (int i = 0; i < 8; ++i) af[i] = *(const bf16x8*)(base + ((a_rd + i * 2048) ^ 64));
; #pragma unroll
;       for (int mi = 0; mi < 8; ++mi)
; #pragma unroll
;         for (int ni = 0; ni < 4; ++ni) acc[mi][ni] = MFMA16(b1[ni], af[mi], acc[mi][ni]);
;     }
;     if (more) {
;       char* nb = smem + ((kt + 1) & 1) * 32768 + lds_w;
; #pragma unroll
;       for (int i = 0; i < 8; ++i) *(u32x4*)(nb + i * 4096) = ra[i];
;     }
;     __syncthreads();
;   }
; #pragma unroll
;   for (int mi = 0; mi < 8; ++mi)
; #pragma unroll
;     for (int ni = 0; ni < 4; ++ni)
;       epi(m0 + wm * 128 + mi * 16 + l15, n0 + wn * 64 + ni * 16 + quad * 4, acc[mi][ni]);
;   DEVI void operator()(int m, int n, f32x4 v) const {
;     if (m >= L) return;
;     float* h = hfrow(p, m) + n;
;     const float* src = (first && m >= 16) ? p.in[0] + (size_t)(m - 16) * 1024 + n : h;
;     f32x4 o = *(const f32x4*)src;
;     o = o * ALPHA + v;
;     *(f32x4*)h = o;
;   }
	v_mfma_f32_16x16x32_bf16 v[14:17], v[14:17], v[62:65], v[138:141]
	s_nop 2
	global_load_dwordx4 v[138:141], v[82:83], off offset:3072
	v_mfma_f32_16x16x32_bf16 v[10:13], v[10:13], v[62:65], v[134:137]
	s_nop 2
	global_load_dwordx4 v[134:137], v[54:55], off offset:3072
	v_add_co_u32_e32 v82, vcc, 0x5f000, v162
	v_mfma_f32_16x16x32_bf16 v[158:161], v[6:9], v[150:153], v[98:101]
	s_nop 0
	v_addc_co_u32_e32 v83, vcc, 0, v163, vcc
	ds_read_b128 v[54:57], v0 offset:32768
	v_mfma_f32_16x16x32_bf16 v[6:9], v[6:9], v[62:65], v[130:133]
	s_nop 2
	global_load_dwordx4 v[130:133], v[82:83], off offset:3072
	v_add_co_u32_e32 v82, vcc, 0x7f000, v162
	v_mfma_f32_16x16x32_bf16 v[150:153], v[2:5], v[150:153], v[118:121]
	s_nop 0
	v_addc_co_u32_e32 v83, vcc, 0, v163, vcc
	global_load_dwordx4 v[180:183], v[82:83], off offset:3072
	v_mfma_f32_16x16x32_bf16 v[2:5], v[2:5], v[62:65], v[126:129]
	ds_read_b128 v[62:65], v0 offset:34816
	s_waitcnt vmcnt(3) lgkmcnt(1)
	v_mfma_f32_16x16x32_bf16 v[126:129], v[138:141], v[54:57], v[122:125]
	s_waitcnt vmcnt(2)
	v_mfma_f32_16x16x32_bf16 v[122:125], v[134:137], v[54:57], v[114:117]
	s_waitcnt vmcnt(1)
	v_mfma_f32_16x16x32_bf16 v[118:121], v[130:133], v[54:57], v[110:113]
	s_waitcnt vmcnt(0)
	v_mfma_f32_16x16x32_bf16 v[114:117], v[180:183], v[54:57], v[106:109]
	s_waitcnt lgkmcnt(0)
	v_mfma_f32_16x16x32_bf16 v[110:113], v[138:141], v[62:65], v[102:105]
	v_mfma_f32_16x16x32_bf16 v[106:109], v[134:137], v[62:65], v[90:93]
	v_mfma_f32_16x16x32_bf16 v[102:105], v[130:133], v[62:65], v[78:81]
	v_mfma_f32_16x16x32_bf16 v[98:101], v[180:183], v[62:65], v[74:77]
	ds_read_b128 v[54:57], v0 offset:36864
	ds_read_b128 v[62:65], v0 offset:38912
	s_waitcnt lgkmcnt(1)
	v_mfma_f32_16x16x32_bf16 v[94:97], v[138:141], v[54:57], v[70:73]
	s_waitcnt lgkmcnt(0)
	v_mfma_f32_16x16x32_bf16 v[74:77], v[134:137], v[62:65], v[22:25]
	v_mfma_f32_16x16x32_bf16 v[70:73], v[130:133], v[62:65], v[30:33]
	s_nop 1
	ds_read_b128 v[22:25], v0 offset:40960
	ds_read_b128 v[30:33], v0 offset:43008
	v_mfma_f32_16x16x32_bf16 v[90:93], v[134:137], v[54:57], v[66:69]
	v_mfma_f32_16x16x32_bf16 v[82:85], v[180:183], v[54:57], v[46:49]
	v_mfma_f32_16x16x32_bf16 v[78:81], v[138:141], v[62:65], v[34:37]
	v_mfma_f32_16x16x32_bf16 v[66:69], v[180:183], v[62:65], v[42:45]
	s_waitcnt lgkmcnt(1)
	v_mfma_f32_16x16x32_bf16 v[62:65], v[138:141], v[22:25], v[18:21]
	s_waitcnt lgkmcnt(0)
	v_mfma_f32_16x16x32_bf16 v[46:49], v[138:141], v[30:33], v[146:149]
	s_nop 0
	ds_read_b128 v[18:21], v0 offset:45056
	s_nop 0
	ds_read_b128 v[146:149], v0 offset:47104
	v_and_b32_e32 v0, 0xffffff80, v168
	v_add_u32_e32 v0, s0, v0
	v_mfma_f32_16x16x32_bf16 v[86:89], v[130:133], v[54:57], v[58:61]
	s_movk_i32 s0, 0x4010
	s_waitcnt lgkmcnt(0)
	s_barrier
	v_mfma_f32_16x16x32_bf16 v[58:61], v[134:137], v[22:25], v[26:29]
	v_mfma_f32_16x16x32_bf16 v[54:57], v[130:133], v[22:25], v[38:41]
	v_mfma_f32_16x16x32_bf16 v[50:53], v[180:183], v[22:25], v[50:53]
	v_mfma_f32_16x16x32_bf16 v[42:45], v[134:137], v[30:33], v[154:157]
	v_mfma_f32_16x16x32_bf16 v[38:41], v[130:133], v[30:33], v[158:161]
	v_mfma_f32_16x16x32_bf16 v[34:37], v[180:183], v[30:33], v[150:153]
	v_mfma_f32_16x16x32_bf16 v[30:33], v[138:141], v[18:21], v[164:167]
	v_mfma_f32_16x16x32_bf16 v[26:29], v[134:137], v[18:21], v[172:175]
	v_mfma_f32_16x16x32_bf16 v[22:25], v[130:133], v[18:21], v[176:179]
	v_mfma_f32_16x16x32_bf16 v[18:21], v[180:183], v[18:21], v[142:145]
	v_mfma_f32_16x16x32_bf16 v[14:17], v[138:141], v[146:149], v[14:17]
	v_mfma_f32_16x16x32_bf16 v[10:13], v[134:137], v[146:149], v[10:13]
	v_mfma_f32_16x16x32_bf16 v[6:9], v[130:133], v[146:149], v[6:9]
	v_and_or_b32 v132, v168, 15, v0
	v_lshl_or_b32 v130, v169, 2, v170
	v_cmp_gt_i32_e32 vcc, s0, v132
	v_mfma_f32_16x16x32_bf16 v[2:5], v[180:183], v[146:149], v[2:5]
	v_ashrrev_i32_e32 v131, 31, v130
	s_and_saveexec_b64 s[0:1], vcc
	s_cbranch_execz .LBB0_1841
	v_lshlrev_b32_e32 v134, 10, v132
	v_add_u32_e32 v136, -16, v132
	v_mov_b32_e32 v137, v1
	v_ashrrev_i32_e32 v135, 31, v134
	v_lshlrev_b64 v[136:137], 12, v[136:137]
	v_lshl_add_u64 v[134:135], v[134:135], 2, s[34:35]
	v_lshl_add_u64 v[136:137], s[26:27], 0, v[136:137]
	v_cmp_gt_i32_e32 vcc, 16, v132
	s_nop 1
	v_cndmask_b32_e32 v135, v137, v135, vcc
	v_cndmask_b32_e32 v134, v136, v134, vcc
	v_lshl_add_u64 v[138:139], v[130:131], 2, v[134:135]
	global_load_dwordx4 v[134:137], v[138:139], off
	s_waitcnt vmcnt(0)
	v_pk_fma_f32 v[128:129], v[136:137], s[66:67], v[128:129] op_sel_hi:[1,0,1]
	v_pk_fma_f32 v[126:127], v[134:135], s[66:67], v[126:127] op_sel_hi:[1,0,1]
	global_store_dwordx4 v[138:139], v[126:129], off
	global_load_dwordx4 v[126:129], v[138:139], off offset:64
	s_waitcnt vmcnt(0)
	v_pk_fma_f32 v[124:125], v[128:129], s[66:67], v[124:125] op_sel_hi:[1,0,1]
	v_pk_fma_f32 v[122:123], v[126:127], s[66:67], v[122:123] op_sel_hi:[1,0,1]
	global_store_dwordx4 v[138:139], v[122:125], off offset:64
	global_load_dwordx4 v[122:125], v[138:139], off offset:128
	s_waitcnt vmcnt(0)
	v_pk_fma_f32 v[120:121], v[124:125], s[66:67], v[120:121] op_sel_hi:[1,0,1]
	v_pk_fma_f32 v[118:119], v[122:123], s[66:67], v[118:119] op_sel_hi:[1,0,1]
	global_store_dwordx4 v[138:139], v[118:121], off offset:128
	global_load_dwordx4 v[118:121], v[138:139], off offset:192
	s_waitcnt vmcnt(0)
	v_pk_fma_f32 v[116:117], v[120:121], s[66:67], v[116:117] op_sel_hi:[1,0,1]
	v_pk_fma_f32 v[114:115], v[118:119], s[66:67], v[114:115] op_sel_hi:[1,0,1]
	global_store_dwordx4 v[138:139], v[114:117], off offset:192
